# cost-weighted VALU spacing: first 11 row-sum adds interleaved with the exp block (same summation order, second accumulator register)
# speedup vs baseline: 1.0020x; 1.0020x over previous
; template <bool WIN>
; __device__ __forceinline__ void partialSM(f32x16& p0, f32x16& p1, float& m_reg, float& mn, float& alpha) {
;   constexpr float C = SCALE * 1.4426950408889634f;
;   float pmax = p0[0];
; #pragma unroll
;   for (int r = 1; r < 16; ++r) pmax = fmaxf(pmax, p0[r]);
; #pragma unroll
;   for (int r = 0; r < 16; ++r) pmax = fmaxf(pmax, p1[r]);
;   { auto rr = __builtin_amdgcn_permlane32_swap(__float_as_uint(pmax), __float_as_uint(pmax), false, false);
;     pmax = fmaxf(__uint_as_float(rr[0]), __uint_as_float(rr[1])); }
;   if (__builtin_expect(__all(pmax - m_reg <= THR / SCALE), 1)) { mn = m_reg; alpha = 1.f; }
;   else { mn = fmaxf(m_reg, pmax); alpha = __builtin_amdgcn_exp2f((m_reg - mn) * C); m_reg = mn; }
;   float mnC = -mn * C;
; #pragma unroll
;   for (int r = 0; r < 16; ++r) p0[r] = fmaf(p0[r], C, mnC);
; #pragma unroll
;   for (int r = 0; r < 16; ++r) p1[r] = fmaf(p1[r], C, mnC);
; #pragma unroll
;   for (int r = 0; r < 16; ++r) p0[r] = __builtin_amdgcn_exp2f(p0[r]);
; }
; __device__ __forceinline__ void finishSM(f32x16& p0, f32x16& p1, float alpha, float& l_reg, bf16x8& pa0, bf16x8& pa1, bf16x8& pa2, bf16x8& pa3) {
; #pragma unroll
;   for (int r = 0; r < 16; ++r) p1[r] = __builtin_amdgcn_exp2f(p1[r]);
;   float ps = 0;
; #pragma unroll
;   for (int r = 0; r < 16; ++r) ps += p0[r];
; #pragma unroll
;   for (int r = 0; r < 16; ++r) ps += p1[r];
;   { auto rr = __builtin_amdgcn_permlane32_swap(__float_as_uint(ps), __float_as_uint(ps), false, false);
;     ps = __uint_as_float(rr[0]) + __uint_as_float(rr[1]); }
;   l_reg = l_reg * alpha + ps;
;     ...
;   PK4(p0, 0, pa0); PK4(p0, 8, pa1); PK4(p1, 0, pa2); PK4(p1, 8, pa3);
;     ...
; }
; template <bool WIN>
; __device__ __forceinline__ void qkt(f32x16& p0, f32x16& p1, const bf16_t* Ks, const bf16x8* qr, int r32, int hi, int dq) {
;   p0 = f32x16{}; p1 = f32x16{};
;   if (WIN) {
;     const int t = 4 * hi - dq + 128;
; #pragma unroll
;     for (int r = 0; r < 16; ++r) { const unsigned d0 = (unsigned)(t + (r & 3) + 8 * (r >> 2)), d1 = d0 + 32u;
;       p0[r] = d0 > 256u ? -1e30f : 0.f; p1[r] = d1 > 256u ? -1e30f : 0.f; }
;   }
; #pragma unroll
;   for (int d0 = 0; d0 < 8; ++d0) { int cb = (d0 * 16 + hi * 8) * 2;
;     bf16x8 b0 = *reinterpret_cast<const bf16x8*>((const char*)Ks + KSWZ(r32, cb));
;     bf16x8 b1 = *reinterpret_cast<const bf16x8*>((const char*)Ks + KSWZ(32 + r32, cb));
.LBB0_643:
	s_and_b32 s69, s68, 1
	s_xor_b32 s33, s69, 1
	s_lshl_b32 s0, s33, 14
	s_add_i32 s0, s35, s0
	v_lshl_add_u64 v[254:255], s[22:23], 0, v[206:207]
	s_mov_b32 m0, s0
	s_nop 0
	global_load_lds_dwordx4 v[254:255], off
	v_lshl_add_u64 v[254:255], s[22:23], 0, v[204:205]
	s_add_i32 m0, s0, 0x400
	s_nop 0
	global_load_lds_dwordx4 v[254:255], off
	s_setprio 1
	s_lshl_b32 s0, s69, 14
	v_add3_u32 v0, s0, v209, v199
	ds_read_b128 v[130:133], v0
	ds_read_b128 v[134:137], v0 offset:8192
	v_add3_u32 v0, s0, v210, v199
	ds_read_b128 v[232:235], v0
	ds_read_b128 v[236:239], v0 offset:8192
	v_add3_u32 v0, s0, v211, v199
	ds_read_b128 v[246:249], v0
	ds_read_b128 v[250:253], v0 offset:8192
	s_waitcnt lgkmcnt(4)
	v_mfma_f32_32x32x16_bf16 v[146:161], v[130:133], v[162:165], 0
	v_mfma_f32_32x32x16_bf16 v[130:145], v[134:137], v[162:165], 0
	s_waitcnt lgkmcnt(2)
	v_mfma_f32_32x32x16_bf16 v[146:161], v[232:235], v[166:169], v[146:161]
	v_mfma_f32_32x32x16_bf16 v[130:145], v[236:239], v[166:169], v[130:145]
	v_add3_u32 v0, s0, v212, v199
	ds_read_b128 v[232:235], v0
	ds_read_b128 v[236:239], v0 offset:8192
	s_waitcnt lgkmcnt(2)
	v_mfma_f32_32x32x16_bf16 v[146:161], v[246:249], v[170:173], v[146:161]
	v_mfma_f32_32x32x16_bf16 v[130:145], v[250:253], v[170:173], v[130:145]
	v_add3_u32 v0, s0, v213, v199
	ds_read_b128 v[246:249], v0
	ds_read_b128 v[250:253], v0 offset:8192
	s_waitcnt lgkmcnt(2)
	v_mfma_f32_32x32x16_bf16 v[146:161], v[232:235], v[174:177], v[146:161]
	v_mfma_f32_32x32x16_bf16 v[130:145], v[236:239], v[174:177], v[130:145]
	v_add3_u32 v0, s0, v214, v199
	ds_read_b128 v[232:235], v0
	ds_read_b128 v[236:239], v0 offset:8192
	s_waitcnt lgkmcnt(2)
	v_mfma_f32_32x32x16_bf16 v[146:161], v[246:249], v[178:181], v[146:161]
	v_mfma_f32_32x32x16_bf16 v[130:145], v[250:253], v[178:181], v[130:145]
	v_add3_u32 v0, s0, v215, v199
	ds_read_b128 v[246:249], v0
	ds_read_b128 v[250:253], v0 offset:8192
	s_waitcnt lgkmcnt(2)
	v_mfma_f32_32x32x16_bf16 v[146:161], v[232:235], v[182:185], v[146:161]
	v_mfma_f32_32x32x16_bf16 v[130:145], v[236:239], v[182:185], v[130:145]
	v_add3_u32 v0, s0, v216, v199
	ds_read_b128 v[232:235], v0
	ds_read_b128 v[236:239], v0 offset:8192
	s_waitcnt lgkmcnt(2)
	v_mfma_f32_32x32x16_bf16 v[146:161], v[246:249], v[186:189], v[146:161]
	v_mfma_f32_32x32x16_bf16 v[130:145], v[250:253], v[186:189], v[130:145]
	s_waitcnt lgkmcnt(0)
	v_mfma_f32_32x32x16_bf16 v[146:161], v[232:235], v[190:193], v[146:161]
	v_mfma_f32_32x32x16_bf16 v[130:145], v[236:239], v[190:193], v[130:145]
	s_setprio 0
	s_nop 7
	s_nop 3
	v_max3_f32 v0, v146, v147, v148
	v_max3_f32 v231, v130, v131, v132
	v_max3_f32 v0, v0, v149, v150
	v_max3_f32 v231, v231, v133, v134
	v_max3_f32 v0, v0, v151, v152
	v_max3_f32 v231, v231, v135, v136
	v_max3_f32 v0, v0, v153, v154
	v_max3_f32 v231, v231, v137, v138
	v_max3_f32 v0, v0, v155, v156
	v_max3_f32 v231, v231, v139, v140
	v_max3_f32 v0, v0, v157, v158
	v_max3_f32 v231, v231, v141, v142
	v_max3_f32 v0, v0, v159, v160
	v_max3_f32 v231, v231, v143, v144
	v_max3_f32 v0, v0, v161, v231
	v_max_f32_e32 v0, v0, v145
	v_mov_b32_e32 v231, v0
	s_nop 1
	v_permlane32_swap_b32_e32 v0, v231
	v_max_f32_e32 v0, v0, v231
	v_sub_f32_e32 v231, v0, v229
	s_mov_b32 s0, 0x42b504f3
	v_cmp_ge_f32_e32 vcc, s0, v231
	v_max_f32_e32 v232, v229, v0
	s_cmp_eq_u64 vcc, exec
	s_cselect_b64 vcc, -1, 0
	v_sub_f32_e32 v0, v229, v232
	v_cndmask_b32_e32 v229, v232, v229, vcc
	v_mul_f32_e32 v231, 0xbe0293ee, v229
	v_fmamk_f32 v146, v146, 0x3e0293ee, v231
	v_fmamk_f32 v147, v147, 0x3e0293ee, v231
	v_fmamk_f32 v148, v148, 0x3e0293ee, v231
	v_fmamk_f32 v149, v149, 0x3e0293ee, v231
	v_fmamk_f32 v150, v150, 0x3e0293ee, v231
	v_fmamk_f32 v151, v151, 0x3e0293ee, v231
	v_fmamk_f32 v152, v152, 0x3e0293ee, v231
	v_fmamk_f32 v153, v153, 0x3e0293ee, v231
	v_fmamk_f32 v154, v154, 0x3e0293ee, v231
	v_fmamk_f32 v155, v155, 0x3e0293ee, v231
	v_fmamk_f32 v156, v156, 0x3e0293ee, v231
	v_fmamk_f32 v157, v157, 0x3e0293ee, v231
	v_fmamk_f32 v158, v158, 0x3e0293ee, v231
	v_fmamk_f32 v159, v159, 0x3e0293ee, v231
	v_fmamk_f32 v160, v160, 0x3e0293ee, v231
	v_fmamk_f32 v161, v161, 0x3e0293ee, v231
	v_fmamk_f32 v130, v130, 0x3e0293ee, v231
	v_fmamk_f32 v131, v131, 0x3e0293ee, v231
	v_fmamk_f32 v132, v132, 0x3e0293ee, v231
	v_fmamk_f32 v133, v133, 0x3e0293ee, v231
	v_fmamk_f32 v134, v134, 0x3e0293ee, v231
	v_fmamk_f32 v135, v135, 0x3e0293ee, v231
	v_fmamk_f32 v136, v136, 0x3e0293ee, v231
	v_fmamk_f32 v137, v137, 0x3e0293ee, v231
	v_fmamk_f32 v138, v138, 0x3e0293ee, v231
	v_fmamk_f32 v139, v139, 0x3e0293ee, v231
	v_fmamk_f32 v140, v140, 0x3e0293ee, v231
	v_fmamk_f32 v141, v141, 0x3e0293ee, v231
	v_fmamk_f32 v142, v142, 0x3e0293ee, v231
	v_fmamk_f32 v143, v143, 0x3e0293ee, v231
	v_fmamk_f32 v144, v144, 0x3e0293ee, v231
	v_fmac_f32_e32 v231, 0x3e0293ee, v145
	v_exp_f32_e32 v145, v146
	v_exp_f32_e32 v146, v147
	v_exp_f32_e32 v147, v148
	v_exp_f32_e32 v148, v149
	v_add_f32_e32 v232, v146, v145
	v_exp_f32_e32 v149, v150
	v_add_f32_e32 v232, v147, v232
	v_exp_f32_e32 v150, v151
	v_add_f32_e32 v232, v148, v232
	v_exp_f32_e32 v151, v152
	v_add_f32_e32 v232, v149, v232
	v_exp_f32_e32 v152, v153
	v_add_f32_e32 v232, v150, v232
	v_exp_f32_e32 v153, v154
	v_add_f32_e32 v232, v151, v232
	v_exp_f32_e32 v154, v155
	v_add_f32_e32 v232, v152, v232
	v_exp_f32_e32 v155, v156
	v_add_f32_e32 v232, v153, v232
	v_exp_f32_e32 v156, v157
	v_add_f32_e32 v232, v154, v232
	v_exp_f32_e32 v157, v158
	v_add_f32_e32 v232, v155, v232
	v_exp_f32_e32 v158, v159
; __device__ __forceinline__ void finishSM(f32x16& p0, f32x16& p1, float alpha, float& l_reg, bf16x8& pa0, bf16x8& pa1, bf16x8& pa2, bf16x8& pa3) {
; #pragma unroll
;   for (int r = 0; r < 16; ++r) p1[r] = __builtin_amdgcn_exp2f(p1[r]);
;   float ps = 0;
; #pragma unroll
;   for (int r = 0; r < 16; ++r) ps += p0[r];
; #pragma unroll
;   for (int r = 0; r < 16; ++r) ps += p1[r];
;   { auto rr = __builtin_amdgcn_permlane32_swap(__float_as_uint(ps), __float_as_uint(ps), false, false);
;     ps = __uint_as_float(rr[0]) + __uint_as_float(rr[1]); }
;   l_reg = l_reg * alpha + ps;
;     ...
;   PK4(p0, 0, pa0); PK4(p0, 8, pa1); PK4(p1, 0, pa2); PK4(p1, 8, pa3);
;     ...
; }
	v_add_f32_e32 v232, v156, v232
	v_exp_f32_e32 v159, v160
	v_exp_f32_e32 v160, v161
	v_exp_f32_e32 v161, v134
	v_exp_f32_e32 v130, v130
	v_add_f32_e32 v134, v157, v232
	v_exp_f32_e32 v131, v131
	v_add_f32_e32 v134, v158, v134
	v_exp_f32_e32 v132, v132
	v_add_f32_e32 v134, v159, v134
	v_exp_f32_e32 v133, v133
	v_add_f32_e32 v134, v160, v134
	v_add_f32_e32 v134, v130, v134
	v_exp_f32_e32 v233, v135
	v_add_f32_e32 v134, v131, v134
	v_exp_f32_e32 v234, v136
	v_add_f32_e32 v134, v132, v134
	v_exp_f32_e32 v235, v137
	v_add_f32_e32 v134, v133, v134
	v_exp_f32_e32 v138, v138
	v_add_f32_e32 v134, v161, v134
	v_exp_f32_e32 v139, v139
	v_add_f32_e32 v134, v233, v134
	v_exp_f32_e32 v140, v140
	v_add_f32_e32 v134, v234, v134
	v_exp_f32_e32 v141, v141
	v_add_f32_e32 v134, v235, v134
	v_exp_f32_e32 v236, v142
	v_add_f32_e32 v134, v138, v134
	v_exp_f32_e32 v237, v143
	v_add_f32_e32 v134, v139, v134
	v_exp_f32_e32 v238, v144
	v_add_f32_e32 v134, v140, v134
	v_mul_f32_e32 v0, 0x3e0293ee, v0
	v_exp_f32_e32 v239, v231
	v_add_f32_e32 v134, v141, v134
	v_exp_f32_e32 v0, v0
	v_add_f32_e32 v134, v236, v134
	v_add_f32_e32 v134, v237, v134
	v_add_f32_e32 v134, v238, v134
	v_add_f32_e32 v231, v239, v134
	v_cndmask_b32_e64 v0, v0, 1.0, vcc
	v_mov_b32_e32 v232, v231
	v_cvt_pk_bf16_f32 v134, v145, v146
	v_cvt_pk_bf16_f32 v135, v147, v148
	v_cvt_pk_bf16_f32 v136, v149, v150
	v_cvt_pk_bf16_f32 v137, v151, v152
	v_cvt_pk_bf16_f32 v142, v153, v154
	v_cvt_pk_bf16_f32 v143, v155, v156
	v_cvt_pk_bf16_f32 v144, v157, v158
	v_cvt_pk_bf16_f32 v145, v159, v160
	v_cvt_pk_bf16_f32 v130, v130, v131
	v_cvt_pk_bf16_f32 v131, v132, v133
	v_cvt_pk_bf16_f32 v132, v161, v233
	v_cvt_pk_bf16_f32 v133, v234, v235
	v_cvt_pk_bf16_f32 v138, v138, v139
	v_cvt_pk_bf16_f32 v139, v140, v141
	v_cvt_pk_bf16_f32 v140, v236, v237
	v_cvt_pk_bf16_f32 v141, v238, v239
	v_permlane32_swap_b32_e32 v231, v232
	v_permlane32_swap_b32_e32 v134, v136
	v_permlane32_swap_b32_e32 v135, v137
	v_permlane32_swap_b32_e32 v142, v144
	v_permlane32_swap_b32_e32 v143, v145
	v_permlane32_swap_b32_e32 v130, v132
	v_permlane32_swap_b32_e32 v131, v133
	v_permlane32_swap_b32_e32 v138, v140
	v_permlane32_swap_b32_e32 v139, v141
	v_cmp_gt_f32_e32 vcc, 1.0, v0
	s_cbranch_vccz .LBB0_649
	s_and_saveexec_b64 s[0:1], s[6:7]
	ds_write_b32 v228, v0 offset:128
	s_or_b64 exec, exec, s[0:1]
	s_waitcnt lgkmcnt(0)
	v_add_u32_e32 v146, s67, v223
	ds_read_b128 v[158:161], v146 offset:224
	ds_read_b128 v[154:157], v146 offset:192
	ds_read_b128 v[150:153], v146 offset:160
	ds_read_b128 v[146:149], v146 offset:128
	s_waitcnt lgkmcnt(0)
	v_pk_mul_f32 v[126:127], v[126:127], v[158:159]
	v_pk_mul_f32 v[122:123], v[122:123], v[154:155]
	v_pk_mul_f32 v[118:119], v[118:119], v[150:151]
	v_pk_mul_f32 v[128:129], v[128:129], v[160:161]
	v_pk_mul_f32 v[124:125], v[124:125], v[156:157]
	v_pk_mul_f32 v[120:121], v[120:121], v[152:153]
	v_pk_mul_f32 v[116:117], v[116:117], v[148:149]
	v_pk_mul_f32 v[114:115], v[114:115], v[146:147]
	v_pk_mul_f32 v[110:111], v[110:111], v[158:159]
	v_pk_mul_f32 v[106:107], v[106:107], v[154:155]
	v_pk_mul_f32 v[102:103], v[102:103], v[150:151]
	v_pk_mul_f32 v[112:113], v[112:113], v[160:161]
	v_pk_mul_f32 v[108:109], v[108:109], v[156:157]
	v_pk_mul_f32 v[104:105], v[104:105], v[152:153]
	v_pk_mul_f32 v[100:101], v[100:101], v[148:149]
	v_pk_mul_f32 v[98:99], v[98:99], v[146:147]
	v_pk_mul_f32 v[94:95], v[94:95], v[158:159]
	v_pk_mul_f32 v[90:91], v[90:91], v[154:155]
	v_pk_mul_f32 v[86:87], v[86:87], v[150:151]
	v_pk_mul_f32 v[96:97], v[96:97], v[160:161]
	v_pk_mul_f32 v[92:93], v[92:93], v[156:157]
	v_pk_mul_f32 v[88:89], v[88:89], v[152:153]
	v_pk_mul_f32 v[84:85], v[84:85], v[148:149]
	v_pk_mul_f32 v[82:83], v[82:83], v[146:147]
	v_pk_mul_f32 v[78:79], v[78:79], v[158:159]
	v_pk_mul_f32 v[74:75], v[74:75], v[154:155]
	v_pk_mul_f32 v[70:71], v[70:71], v[150:151]
	v_pk_mul_f32 v[80:81], v[80:81], v[160:161]
	v_pk_mul_f32 v[76:77], v[76:77], v[156:157]
	v_pk_mul_f32 v[72:73], v[72:73], v[152:153]
	v_pk_mul_f32 v[68:69], v[68:69], v[148:149]
	v_pk_mul_f32 v[66:67], v[66:67], v[146:147]
	v_pk_mul_f32 v[62:63], v[62:63], v[158:159]
	v_pk_mul_f32 v[58:59], v[58:59], v[154:155]
	v_pk_mul_f32 v[54:55], v[54:55], v[150:151]
	v_pk_mul_f32 v[64:65], v[64:65], v[160:161]
	v_pk_mul_f32 v[60:61], v[60:61], v[156:157]
	v_pk_mul_f32 v[56:57], v[56:57], v[152:153]
	v_pk_mul_f32 v[52:53], v[52:53], v[148:149]
	v_pk_mul_f32 v[50:51], v[50:51], v[146:147]
	v_pk_mul_f32 v[46:47], v[46:47], v[158:159]
	v_pk_mul_f32 v[42:43], v[42:43], v[154:155]
	v_pk_mul_f32 v[38:39], v[38:39], v[150:151]
	v_pk_mul_f32 v[48:49], v[48:49], v[160:161]
	v_pk_mul_f32 v[44:45], v[44:45], v[156:157]
	v_pk_mul_f32 v[40:41], v[40:41], v[152:153]
	v_pk_mul_f32 v[36:37], v[36:37], v[148:149]
	v_pk_mul_f32 v[34:35], v[34:35], v[146:147]
	v_pk_mul_f32 v[30:31], v[30:31], v[158:159]
	v_pk_mul_f32 v[26:27], v[26:27], v[154:155]
	v_pk_mul_f32 v[22:23], v[22:23], v[150:151]
	v_pk_mul_f32 v[32:33], v[32:33], v[160:161]
	v_pk_mul_f32 v[28:29], v[28:29], v[156:157]
	v_pk_mul_f32 v[24:25], v[24:25], v[152:153]
	v_pk_mul_f32 v[20:21], v[20:21], v[148:149]
	v_pk_mul_f32 v[18:19], v[18:19], v[146:147]
	v_pk_mul_f32 v[14:15], v[14:15], v[158:159]
	v_pk_mul_f32 v[10:11], v[10:11], v[154:155]
	v_pk_mul_f32 v[6:7], v[6:7], v[150:151]
	v_pk_mul_f32 v[16:17], v[16:17], v[160:161]
	v_pk_mul_f32 v[12:13], v[12:13], v[156:157]
	v_pk_mul_f32 v[8:9], v[8:9], v[152:153]
	v_pk_mul_f32 v[4:5], v[4:5], v[148:149]
	v_pk_mul_f32 v[2:3], v[2:3], v[146:147]

; template <bool WIN>
; __device__ __forceinline__ void partialSM(f32x16& p0, f32x16& p1, float& m_reg, float& mn, float& alpha) {
;   constexpr float C = SCALE * 1.4426950408889634f;
;   float pmax = p0[0];
; #pragma unroll
;   for (int r = 1; r < 16; ++r) pmax = fmaxf(pmax, p0[r]);
; #pragma unroll
;   for (int r = 0; r < 16; ++r) pmax = fmaxf(pmax, p1[r]);
;   { auto rr = __builtin_amdgcn_permlane32_swap(__float_as_uint(pmax), __float_as_uint(pmax), false, false);
;     pmax = fmaxf(__uint_as_float(rr[0]), __uint_as_float(rr[1])); }
;   if (__builtin_expect(__all(pmax - m_reg <= THR / SCALE), 1)) { mn = m_reg; alpha = 1.f; }
;   else { mn = fmaxf(m_reg, pmax); alpha = __builtin_amdgcn_exp2f((m_reg - mn) * C); m_reg = mn; }
;   float mnC = -mn * C;
; #pragma unroll
;   for (int r = 0; r < 16; ++r) p0[r] = fmaf(p0[r], C, mnC);
; #pragma unroll
;   for (int r = 0; r < 16; ++r) p1[r] = fmaf(p1[r], C, mnC);
; #pragma unroll
;   for (int r = 0; r < 16; ++r) p0[r] = __builtin_amdgcn_exp2f(p0[r]);
; }
; __device__ __forceinline__ void finishSM(f32x16& p0, f32x16& p1, float alpha, float& l_reg, bf16x8& pa0, bf16x8& pa1, bf16x8& pa2, bf16x8& pa3) {
; #pragma unroll
;   for (int r = 0; r < 16; ++r) p1[r] = __builtin_amdgcn_exp2f(p1[r]);
;   float ps = 0;
; #pragma unroll
;   for (int r = 0; r < 16; ++r) ps += p0[r];
; #pragma unroll
;   for (int r = 0; r < 16; ++r) ps += p1[r];
; template <bool WIN>
; __device__ __forceinline__ void qkt(f32x16& p0, f32x16& p1, const bf16_t* Ks, const bf16x8* qr, int r32, int hi, int dq) {
;   p0 = f32x16{}; p1 = f32x16{};
;   if (WIN) {
;     const int t = 4 * hi - dq + 128;
; #pragma unroll
;     for (int r = 0; r < 16; ++r) { const unsigned d0 = (unsigned)(t + (r & 3) + 8 * (r >> 2)), d1 = d0 + 32u;
;       p0[r] = d0 > 256u ? -1e30f : 0.f; p1[r] = d1 > 256u ? -1e30f : 0.f; }
;   }
; #pragma unroll
;   for (int d0 = 0; d0 < 8; ++d0) { int cb = (d0 * 16 + hi * 8) * 2;
;     bf16x8 b0 = *reinterpret_cast<const bf16x8*>((const char*)Ks + KSWZ(r32, cb));
;     bf16x8 b1 = *reinterpret_cast<const bf16x8*>((const char*)Ks + KSWZ(32 + r32, cb));
;     p0 = __builtin_amdgcn_mfma_f32_32x32x16_bf16(b0, qr[d0], p0, 0, 0, 0);
;     p1 = __builtin_amdgcn_mfma_f32_32x32x16_bf16(b1, qr[d0], p1, 0, 0, 0); }
.Lpl_top:
	s_and_b32 s69, s68, 1
	s_setprio 1
	s_lshl_b32 s0, s69, 14
	v_add3_u32 v0, s0, v209, v199
	ds_read_b128 v[130:133], v0
	ds_read_b128 v[134:137], v0 offset:8192
	v_add3_u32 v0, s0, v210, v199
	ds_read_b128 v[232:235], v0
	ds_read_b128 v[236:239], v0 offset:8192
	v_add3_u32 v0, s0, v211, v199
	ds_read_b128 v[246:249], v0
	ds_read_b128 v[250:253], v0 offset:8192
	s_waitcnt lgkmcnt(4)
	v_mfma_f32_32x32x16_bf16 v[146:161], v[130:133], v[162:165], 0
	v_mfma_f32_32x32x16_bf16 v[130:145], v[134:137], v[162:165], 0
	s_waitcnt lgkmcnt(2)
	v_mfma_f32_32x32x16_bf16 v[146:161], v[232:235], v[166:169], v[146:161]
	v_mfma_f32_32x32x16_bf16 v[130:145], v[236:239], v[166:169], v[130:145]
	v_add3_u32 v0, s0, v212, v199
	ds_read_b128 v[232:235], v0
	ds_read_b128 v[236:239], v0 offset:8192
	s_waitcnt lgkmcnt(2)
	v_mfma_f32_32x32x16_bf16 v[146:161], v[246:249], v[170:173], v[146:161]
	v_mfma_f32_32x32x16_bf16 v[130:145], v[250:253], v[170:173], v[130:145]
	v_add3_u32 v0, s0, v213, v199
	ds_read_b128 v[246:249], v0
	ds_read_b128 v[250:253], v0 offset:8192
	s_waitcnt lgkmcnt(2)
	v_mfma_f32_32x32x16_bf16 v[146:161], v[232:235], v[174:177], v[146:161]
	v_mfma_f32_32x32x16_bf16 v[130:145], v[236:239], v[174:177], v[130:145]
	v_add3_u32 v0, s0, v214, v199
	ds_read_b128 v[232:235], v0
	ds_read_b128 v[236:239], v0 offset:8192
	s_waitcnt lgkmcnt(2)
	v_mfma_f32_32x32x16_bf16 v[146:161], v[246:249], v[178:181], v[146:161]
	v_mfma_f32_32x32x16_bf16 v[130:145], v[250:253], v[178:181], v[130:145]
	v_add3_u32 v0, s0, v215, v199
	ds_read_b128 v[246:249], v0
	ds_read_b128 v[250:253], v0 offset:8192
	s_waitcnt lgkmcnt(2)
	v_mfma_f32_32x32x16_bf16 v[146:161], v[232:235], v[182:185], v[146:161]
	v_mfma_f32_32x32x16_bf16 v[130:145], v[236:239], v[182:185], v[130:145]
	v_add3_u32 v0, s0, v216, v199
	ds_read_b128 v[232:235], v0
	ds_read_b128 v[236:239], v0 offset:8192
	s_waitcnt lgkmcnt(2)
	v_mfma_f32_32x32x16_bf16 v[146:161], v[246:249], v[186:189], v[146:161]
	v_mfma_f32_32x32x16_bf16 v[130:145], v[250:253], v[186:189], v[130:145]
	s_waitcnt lgkmcnt(0)
	v_mfma_f32_32x32x16_bf16 v[146:161], v[232:235], v[190:193], v[146:161]
	v_mfma_f32_32x32x16_bf16 v[130:145], v[236:239], v[190:193], v[130:145]
	s_setprio 0
	s_nop 7
	s_nop 3
	v_max3_f32 v0, v146, v147, v148
	v_max3_f32 v231, v130, v131, v132
	v_max3_f32 v0, v0, v149, v150
	v_max3_f32 v231, v231, v133, v134
	v_max3_f32 v0, v0, v151, v152
	v_max3_f32 v231, v231, v135, v136
	v_max3_f32 v0, v0, v153, v154
	v_max3_f32 v231, v231, v137, v138
	v_max3_f32 v0, v0, v155, v156
	v_max3_f32 v231, v231, v139, v140
	v_max3_f32 v0, v0, v157, v158
	v_max3_f32 v231, v231, v141, v142
	v_max3_f32 v0, v0, v159, v160
	v_max3_f32 v231, v231, v143, v144
	v_max3_f32 v0, v0, v161, v231
	v_max_f32_e32 v0, v0, v145
	v_mov_b32_e32 v231, v0
	s_nop 1
	v_permlane32_swap_b32_e32 v0, v231
	v_max_f32_e32 v0, v0, v231
	v_sub_f32_e32 v231, v0, v229
	s_mov_b32 s0, 0x42b504f3
	v_cmp_ge_f32_e32 vcc, s0, v231
	v_max_f32_e32 v232, v229, v0
	s_cmp_eq_u64 vcc, exec
	s_cselect_b64 vcc, -1, 0
	v_sub_f32_e32 v0, v229, v232
	v_cndmask_b32_e32 v229, v232, v229, vcc
	v_mul_f32_e32 v231, 0xbe0293ee, v229
	v_fmamk_f32 v146, v146, 0x3e0293ee, v231
	v_fmamk_f32 v147, v147, 0x3e0293ee, v231
	v_fmamk_f32 v148, v148, 0x3e0293ee, v231
	v_fmamk_f32 v149, v149, 0x3e0293ee, v231
	v_fmamk_f32 v150, v150, 0x3e0293ee, v231
	v_fmamk_f32 v151, v151, 0x3e0293ee, v231
	v_fmamk_f32 v152, v152, 0x3e0293ee, v231
	v_fmamk_f32 v153, v153, 0x3e0293ee, v231
	v_fmamk_f32 v154, v154, 0x3e0293ee, v231
	v_fmamk_f32 v155, v155, 0x3e0293ee, v231
	v_fmamk_f32 v156, v156, 0x3e0293ee, v231
	v_fmamk_f32 v157, v157, 0x3e0293ee, v231
	v_fmamk_f32 v158, v158, 0x3e0293ee, v231
	v_fmamk_f32 v159, v159, 0x3e0293ee, v231
	v_fmamk_f32 v160, v160, 0x3e0293ee, v231
	v_fmamk_f32 v161, v161, 0x3e0293ee, v231
	v_fmamk_f32 v130, v130, 0x3e0293ee, v231
	v_fmamk_f32 v131, v131, 0x3e0293ee, v231
	v_fmamk_f32 v132, v132, 0x3e0293ee, v231
	v_fmamk_f32 v133, v133, 0x3e0293ee, v231
	v_fmamk_f32 v134, v134, 0x3e0293ee, v231
	v_fmamk_f32 v135, v135, 0x3e0293ee, v231
	v_fmamk_f32 v136, v136, 0x3e0293ee, v231
	v_fmamk_f32 v137, v137, 0x3e0293ee, v231
	v_fmamk_f32 v138, v138, 0x3e0293ee, v231
	v_fmamk_f32 v139, v139, 0x3e0293ee, v231
	v_fmamk_f32 v140, v140, 0x3e0293ee, v231
	v_fmamk_f32 v141, v141, 0x3e0293ee, v231
	v_fmamk_f32 v142, v142, 0x3e0293ee, v231
	v_fmamk_f32 v143, v143, 0x3e0293ee, v231
	v_fmamk_f32 v144, v144, 0x3e0293ee, v231
	v_fmac_f32_e32 v231, 0x3e0293ee, v145
	v_exp_f32_e32 v145, v146
	v_exp_f32_e32 v146, v147
	v_exp_f32_e32 v147, v148
	v_exp_f32_e32 v148, v149
	v_add_f32_e32 v232, v146, v145
	v_exp_f32_e32 v149, v150
	v_add_f32_e32 v232, v147, v232
	v_exp_f32_e32 v150, v151
	v_add_f32_e32 v232, v148, v232
	v_exp_f32_e32 v151, v152
	v_add_f32_e32 v232, v149, v232
	v_exp_f32_e32 v152, v153
	v_add_f32_e32 v232, v150, v232
	v_exp_f32_e32 v153, v154
	v_add_f32_e32 v232, v151, v232
	v_exp_f32_e32 v154, v155
	v_add_f32_e32 v232, v152, v232
	v_exp_f32_e32 v155, v156
	v_add_f32_e32 v232, v153, v232
	v_exp_f32_e32 v156, v157
	v_add_f32_e32 v232, v154, v232
	v_exp_f32_e32 v157, v158
	v_add_f32_e32 v232, v155, v232
	v_exp_f32_e32 v158, v159
	v_add_f32_e32 v232, v156, v232
	v_exp_f32_e32 v159, v160
	v_exp_f32_e32 v160, v161
	v_exp_f32_e32 v161, v134
	v_exp_f32_e32 v130, v130
	v_add_f32_e32 v134, v157, v232
; __device__ __forceinline__ void finishSM(f32x16& p0, f32x16& p1, float alpha, float& l_reg, bf16x8& pa0, bf16x8& pa1, bf16x8& pa2, bf16x8& pa3) {
; #pragma unroll
;   for (int r = 0; r < 16; ++r) p1[r] = __builtin_amdgcn_exp2f(p1[r]);
;   float ps = 0;
; #pragma unroll
;   for (int r = 0; r < 16; ++r) ps += p0[r];
; #pragma unroll
;   for (int r = 0; r < 16; ++r) ps += p1[r];
;   { auto rr = __builtin_amdgcn_permlane32_swap(__float_as_uint(ps), __float_as_uint(ps), false, false);
;     ps = __uint_as_float(rr[0]) + __uint_as_float(rr[1]); }
;   l_reg = l_reg * alpha + ps;
;     ...
;   PK4(p0, 0, pa0); PK4(p0, 8, pa1); PK4(p1, 0, pa2); PK4(p1, 8, pa3);
;     ...
; }
	v_exp_f32_e32 v131, v131
	v_add_f32_e32 v134, v158, v134
	v_exp_f32_e32 v132, v132
	v_add_f32_e32 v134, v159, v134
	v_exp_f32_e32 v133, v133
	v_add_f32_e32 v134, v160, v134
	v_add_f32_e32 v134, v130, v134
	v_exp_f32_e32 v233, v135
	v_add_f32_e32 v134, v131, v134
	v_exp_f32_e32 v234, v136
	v_add_f32_e32 v134, v132, v134
	v_exp_f32_e32 v235, v137
	v_add_f32_e32 v134, v133, v134
	v_exp_f32_e32 v138, v138
	v_add_f32_e32 v134, v161, v134
	v_exp_f32_e32 v139, v139
	v_add_f32_e32 v134, v233, v134
	v_exp_f32_e32 v140, v140
	v_add_f32_e32 v134, v234, v134
	v_exp_f32_e32 v141, v141
	v_add_f32_e32 v134, v235, v134
	v_exp_f32_e32 v236, v142
	v_add_f32_e32 v134, v138, v134
	v_exp_f32_e32 v237, v143
	v_add_f32_e32 v134, v139, v134
	v_exp_f32_e32 v238, v144
	v_add_f32_e32 v134, v140, v134
	v_mul_f32_e32 v0, 0x3e0293ee, v0
	v_exp_f32_e32 v239, v231
	v_add_f32_e32 v134, v141, v134
	v_exp_f32_e32 v0, v0
	v_add_f32_e32 v134, v236, v134
	v_add_f32_e32 v134, v237, v134
	v_add_f32_e32 v134, v238, v134
	v_add_f32_e32 v231, v239, v134
	v_cndmask_b32_e64 v0, v0, 1.0, vcc
	v_mov_b32_e32 v232, v231
	v_cvt_pk_bf16_f32 v134, v145, v146
	v_cvt_pk_bf16_f32 v135, v147, v148
	v_cvt_pk_bf16_f32 v136, v149, v150
	v_cvt_pk_bf16_f32 v137, v151, v152
	v_cvt_pk_bf16_f32 v142, v153, v154
	v_cvt_pk_bf16_f32 v143, v155, v156
	v_cvt_pk_bf16_f32 v144, v157, v158
	v_cvt_pk_bf16_f32 v145, v159, v160
	v_cvt_pk_bf16_f32 v130, v130, v131
	v_cvt_pk_bf16_f32 v131, v132, v133
	v_cvt_pk_bf16_f32 v132, v161, v233
	v_cvt_pk_bf16_f32 v133, v234, v235
	v_cvt_pk_bf16_f32 v138, v138, v139
	v_cvt_pk_bf16_f32 v139, v140, v141
	v_cvt_pk_bf16_f32 v140, v236, v237
	v_cvt_pk_bf16_f32 v141, v238, v239
	v_permlane32_swap_b32_e32 v231, v232
	v_permlane32_swap_b32_e32 v134, v136
	v_permlane32_swap_b32_e32 v135, v137
	v_permlane32_swap_b32_e32 v142, v144
	v_permlane32_swap_b32_e32 v143, v145
	v_permlane32_swap_b32_e32 v130, v132
	v_permlane32_swap_b32_e32 v131, v133
	v_permlane32_swap_b32_e32 v138, v140
	v_permlane32_swap_b32_e32 v139, v141
	v_cmp_gt_f32_e32 vcc, 1.0, v0
	s_cbranch_vccz .Lpl_649
	s_and_saveexec_b64 s[0:1], s[6:7]
	ds_write_b32 v228, v0 offset:128
	s_or_b64 exec, exec, s[0:1]
	s_waitcnt lgkmcnt(0)
	v_add_u32_e32 v146, s67, v223
	ds_read_b128 v[158:161], v146 offset:224
	ds_read_b128 v[154:157], v146 offset:192
	ds_read_b128 v[150:153], v146 offset:160
	ds_read_b128 v[146:149], v146 offset:128
	s_waitcnt lgkmcnt(0)
	v_pk_mul_f32 v[126:127], v[126:127], v[158:159]
	v_pk_mul_f32 v[122:123], v[122:123], v[154:155]
	v_pk_mul_f32 v[118:119], v[118:119], v[150:151]
	v_pk_mul_f32 v[128:129], v[128:129], v[160:161]
	v_pk_mul_f32 v[124:125], v[124:125], v[156:157]
	v_pk_mul_f32 v[120:121], v[120:121], v[152:153]
	v_pk_mul_f32 v[116:117], v[116:117], v[148:149]
	v_pk_mul_f32 v[114:115], v[114:115], v[146:147]
	v_pk_mul_f32 v[110:111], v[110:111], v[158:159]
	v_pk_mul_f32 v[106:107], v[106:107], v[154:155]
	v_pk_mul_f32 v[102:103], v[102:103], v[150:151]
	v_pk_mul_f32 v[112:113], v[112:113], v[160:161]
	v_pk_mul_f32 v[108:109], v[108:109], v[156:157]
	v_pk_mul_f32 v[104:105], v[104:105], v[152:153]
	v_pk_mul_f32 v[100:101], v[100:101], v[148:149]
	v_pk_mul_f32 v[98:99], v[98:99], v[146:147]
	v_pk_mul_f32 v[94:95], v[94:95], v[158:159]
	v_pk_mul_f32 v[90:91], v[90:91], v[154:155]
	v_pk_mul_f32 v[86:87], v[86:87], v[150:151]
	v_pk_mul_f32 v[96:97], v[96:97], v[160:161]
	v_pk_mul_f32 v[92:93], v[92:93], v[156:157]
	v_pk_mul_f32 v[88:89], v[88:89], v[152:153]
	v_pk_mul_f32 v[84:85], v[84:85], v[148:149]
	v_pk_mul_f32 v[82:83], v[82:83], v[146:147]
	v_pk_mul_f32 v[78:79], v[78:79], v[158:159]
	v_pk_mul_f32 v[74:75], v[74:75], v[154:155]
	v_pk_mul_f32 v[70:71], v[70:71], v[150:151]
	v_pk_mul_f32 v[80:81], v[80:81], v[160:161]
	v_pk_mul_f32 v[76:77], v[76:77], v[156:157]
	v_pk_mul_f32 v[72:73], v[72:73], v[152:153]
	v_pk_mul_f32 v[68:69], v[68:69], v[148:149]
	v_pk_mul_f32 v[66:67], v[66:67], v[146:147]
	v_pk_mul_f32 v[62:63], v[62:63], v[158:159]
	v_pk_mul_f32 v[58:59], v[58:59], v[154:155]
	v_pk_mul_f32 v[54:55], v[54:55], v[150:151]
	v_pk_mul_f32 v[64:65], v[64:65], v[160:161]
	v_pk_mul_f32 v[60:61], v[60:61], v[156:157]
	v_pk_mul_f32 v[56:57], v[56:57], v[152:153]
	v_pk_mul_f32 v[52:53], v[52:53], v[148:149]
	v_pk_mul_f32 v[50:51], v[50:51], v[146:147]
	v_pk_mul_f32 v[46:47], v[46:47], v[158:159]
	v_pk_mul_f32 v[42:43], v[42:43], v[154:155]
	v_pk_mul_f32 v[38:39], v[38:39], v[150:151]
	v_pk_mul_f32 v[48:49], v[48:49], v[160:161]
	v_pk_mul_f32 v[44:45], v[44:45], v[156:157]
	v_pk_mul_f32 v[40:41], v[40:41], v[152:153]
	v_pk_mul_f32 v[36:37], v[36:37], v[148:149]
	v_pk_mul_f32 v[34:35], v[34:35], v[146:147]
	v_pk_mul_f32 v[30:31], v[30:31], v[158:159]
	v_pk_mul_f32 v[26:27], v[26:27], v[154:155]
	v_pk_mul_f32 v[22:23], v[22:23], v[150:151]
	v_pk_mul_f32 v[32:33], v[32:33], v[160:161]
	v_pk_mul_f32 v[28:29], v[28:29], v[156:157]
	v_pk_mul_f32 v[24:25], v[24:25], v[152:153]
	v_pk_mul_f32 v[20:21], v[20:21], v[148:149]
	v_pk_mul_f32 v[18:19], v[18:19], v[146:147]
	v_pk_mul_f32 v[14:15], v[14:15], v[158:159]
	v_pk_mul_f32 v[10:11], v[10:11], v[154:155]
	v_pk_mul_f32 v[6:7], v[6:7], v[150:151]
	v_pk_mul_f32 v[16:17], v[16:17], v[160:161]
	v_pk_mul_f32 v[12:13], v[12:13], v[156:157]
	v_pk_mul_f32 v[8:9], v[8:9], v[152:153]
	v_pk_mul_f32 v[4:5], v[4:5], v[148:149]
	v_pk_mul_f32 v[2:3], v[2:3], v[146:147]
